# fixed softmax shift M=12*max|gq|*max|gk| (runtime bound from QK-norm gains, fallback to running max) for GQA and differential attention steady loops
# speedup vs baseline: 1.0489x; 1.0446x over previous
; #define LAS __attribute__((address_space(3)))
; __device__ __forceinline__ void phase_inproj(const Params& p, int l, unsigned char* smem) {
;     ...
;     LAS float* ropeL = (LAS float*)((LAS unsigned char*)smem + 131072 + 18432);
;     LAS float* gL = ropeL + 2048;
;     {
;         int tid = threadIdx.x; asm volatile("" : "+v"(tid));
;         *(LAS f32x4*)(ropeL + tid * 4) = *(const f32x4*)(p.rope + tid * 4);
;         if (tid < 64) gL[tid] = sel4(p.q_g, l)[tid]; else if (tid < 128) gL[tid] = sel4(p.k_g, l)[tid - 64];
; __device__ __forceinline__ void phase_attn(const Params& p, int l, unsigned char* smem) {
;     const int kind = l % 3;
;     const bool need_ctx = l < 3;
;     bf16_t* sbase = (bf16_t*)smem; float* srpb = (float*)(sbase + 2 * ATT_BUF);
;     int tid = threadIdx.x; asm volatile("" : "+v"(tid));
;     const int lane = tid & 63, w = tid >> 6, lr = lane & 31, lh = lane >> 5;
;     const int b = blockIdx.x & 7, xj = blockIdx.x >> 3, xn = gridDim.x >> 3;
;     if (kind == 0) {
.Lattn_prio_skip:
	v_mov_b32_e32 v0, 0x26800
	ds_read_b128 v[20:23], v0 offset:0
	ds_read_b128 v[24:27], v0 offset:16
	ds_read_b128 v[28:31], v0 offset:32
	ds_read_b128 v[32:35], v0 offset:48
	ds_read_b128 v[36:39], v0 offset:64
	ds_read_b128 v[40:43], v0 offset:80
	ds_read_b128 v[44:47], v0 offset:96
	ds_read_b128 v[48:51], v0 offset:112
	ds_read_b128 v[52:55], v0 offset:128
	ds_read_b128 v[56:59], v0 offset:144
	ds_read_b128 v[60:63], v0 offset:160
	ds_read_b128 v[64:67], v0 offset:176
	ds_read_b128 v[68:71], v0 offset:192
	ds_read_b128 v[72:75], v0 offset:208
	ds_read_b128 v[76:79], v0 offset:224
	ds_read_b128 v[80:83], v0 offset:240
	s_waitcnt lgkmcnt(0)
	v_max3_f32 v2, |v20|, |v21|, |v22|
	v_max3_f32 v2, v2, |v23|, |v24|
	v_max3_f32 v2, v2, |v25|, |v26|
	v_max3_f32 v2, v2, |v27|, |v28|
	v_max3_f32 v2, v2, |v29|, |v30|
	v_max3_f32 v2, v2, |v31|, |v32|
	v_max3_f32 v2, v2, |v33|, |v34|
	v_max3_f32 v2, v2, |v35|, |v36|
	v_max3_f32 v2, v2, |v37|, |v38|
	v_max3_f32 v2, v2, |v39|, |v40|
	v_max3_f32 v2, v2, |v41|, |v42|
	v_max3_f32 v2, v2, |v43|, |v44|
	v_max3_f32 v2, v2, |v45|, |v46|
	v_max3_f32 v2, v2, |v47|, |v48|
	v_max3_f32 v2, v2, |v49|, |v50|
	v_max3_f32 v2, v2, |v51|, |v52|
	v_max3_f32 v2, v2, |v53|, |v54|
	v_max3_f32 v2, v2, |v55|, |v56|
	v_max3_f32 v2, v2, |v57|, |v58|
	v_max3_f32 v2, v2, |v59|, |v60|
	v_max3_f32 v2, v2, |v61|, |v62|
	v_max3_f32 v2, v2, |v63|, |v64|
	v_max3_f32 v2, v2, |v65|, |v66|
	v_max3_f32 v2, v2, |v67|, |v68|
	v_max3_f32 v2, v2, |v69|, |v70|
	v_max3_f32 v2, v2, |v71|, |v72|
	v_max3_f32 v2, v2, |v73|, |v74|
	v_max3_f32 v2, v2, |v75|, |v76|
	v_max3_f32 v2, v2, |v77|, |v78|
	v_max3_f32 v2, v2, |v79|, |v80|
	v_max3_f32 v2, v2, |v81|, |v82|
	v_max_f32_e64 v2, v2, |v83|
	ds_read_b128 v[20:23], v0 offset:256
	ds_read_b128 v[24:27], v0 offset:272
	ds_read_b128 v[28:31], v0 offset:288
	ds_read_b128 v[32:35], v0 offset:304
	ds_read_b128 v[36:39], v0 offset:320
	ds_read_b128 v[40:43], v0 offset:336
	ds_read_b128 v[44:47], v0 offset:352
	ds_read_b128 v[48:51], v0 offset:368
	ds_read_b128 v[52:55], v0 offset:384
	ds_read_b128 v[56:59], v0 offset:400
	ds_read_b128 v[60:63], v0 offset:416
	ds_read_b128 v[64:67], v0 offset:432
	ds_read_b128 v[68:71], v0 offset:448
	ds_read_b128 v[72:75], v0 offset:464
	ds_read_b128 v[76:79], v0 offset:480
	ds_read_b128 v[80:83], v0 offset:496
	s_waitcnt lgkmcnt(0)
	v_max3_f32 v3, |v20|, |v21|, |v22|
	v_max3_f32 v3, v3, |v23|, |v24|
	v_max3_f32 v3, v3, |v25|, |v26|
	v_max3_f32 v3, v3, |v27|, |v28|
	v_max3_f32 v3, v3, |v29|, |v30|
	v_max3_f32 v3, v3, |v31|, |v32|
	v_max3_f32 v3, v3, |v33|, |v34|
	v_max3_f32 v3, v3, |v35|, |v36|
	v_max3_f32 v3, v3, |v37|, |v38|
	v_max3_f32 v3, v3, |v39|, |v40|
	v_max3_f32 v3, v3, |v41|, |v42|
	v_max3_f32 v3, v3, |v43|, |v44|
	v_max3_f32 v3, v3, |v45|, |v46|
	v_max3_f32 v3, v3, |v47|, |v48|
	v_max3_f32 v3, v3, |v49|, |v50|
	v_max3_f32 v3, v3, |v51|, |v52|
	v_max3_f32 v3, v3, |v53|, |v54|
	v_max3_f32 v3, v3, |v55|, |v56|
	v_max3_f32 v3, v3, |v57|, |v58|
	v_max3_f32 v3, v3, |v59|, |v60|
	v_max3_f32 v3, v3, |v61|, |v62|
	v_max3_f32 v3, v3, |v63|, |v64|
	v_max3_f32 v3, v3, |v65|, |v66|
	v_max3_f32 v3, v3, |v67|, |v68|
	v_max3_f32 v3, v3, |v69|, |v70|
	v_max3_f32 v3, v3, |v71|, |v72|
	v_max3_f32 v3, v3, |v73|, |v74|
	v_max3_f32 v3, v3, |v75|, |v76|
	v_max3_f32 v3, v3, |v77|, |v78|
	v_max3_f32 v3, v3, |v79|, |v80|
	v_max3_f32 v3, v3, |v81|, |v82|
	v_max_f32_e64 v3, v3, |v83|
	v_mul_f32_e32 v2, v2, v3
	v_mul_f32_e32 v2, 0x41400000, v2
	s_nop 1
	v_readfirstlane_b32 s4, v2
	s_cmp_gt_u32 s4, 0x42200000
	s_cselect_b32 s4, 0, s4
	s_nop 3
	v_writelane_b32 v255, s4, 40
	s_cmp_lt_i32 s45, 1
	s_mov_b64 s[4:5], -1
	s_barrier
	s_cbranch_scc1 .LBB0_760
	s_cmp_lg_u32 s45, 1
	s_cbranch_scc0 .LBB0_334
	v_readlane_b32 s4, v254, 60
	v_readlane_b32 s5, v254, 61
	s_and_b64 s[4:5], s[4:5], exec
	s_movk_i32 s4, 0x88
	s_cselect_b32 s34, 0x80, s4
	v_readlane_b32 s4, v254, 21
	s_movk_i32 s60, 0x1000
	s_cmp_ge_u32 s4, s34
	s_cbranch_scc1 .LBB0_333
	v_readlane_b32 s4, v253, 0
	v_readlane_b32 s18, v253, 14
	v_readlane_b32 s19, v253, 15
	v_readlane_b32 s5, v253, 1
	v_readlane_b32 s6, v253, 2
	v_readlane_b32 s7, v253, 3
	v_readlane_b32 s8, v253, 4
	v_readlane_b32 s9, v253, 5
	global_load_dword v17, v1, s[18:19]
	v_readlane_b32 s10, v253, 6
	v_readlane_b32 s11, v253, 7
	v_readlane_b32 s12, v253, 8
	v_readlane_b32 s13, v253, 9
	v_readlane_b32 s14, v253, 10
	v_readlane_b32 s15, v253, 11
	v_readlane_b32 s16, v253, 12
	v_readlane_b32 s17, v253, 13
	v_ashrrev_i32_e32 v0, 1, v210
	v_and_b32_e32 v212, 0xffffffe0, v0
	v_lshlrev_b32_e32 v0, 3, v210
	v_readlane_b32 s4, v253, 32
	v_and_b32_e32 v0, 0x1f8, v0
	v_readlane_b32 s5, v253, 33
	v_readlane_b32 s6, v253, 34
	v_readlane_b32 s7, v253, 35
	v_readlane_b32 s8, v253, 36
	v_readlane_b32 s9, v253, 37
	v_readlane_b32 s10, v253, 38
	v_readlane_b32 s11, v253, 39
	v_readlane_b32 s12, v253, 40
	v_readlane_b32 s13, v253, 41
	v_readlane_b32 s14, v253, 42
	v_readlane_b32 s15, v253, 43
	v_readlane_b32 s16, v253, 44
	v_readlane_b32 s17, v253, 45
	v_readlane_b32 s18, v253, 46
	v_readlane_b32 s19, v253, 47
	v_lshl_add_u64 v[214:215], s[12:13], 0, v[0:1]
	v_and_b32_e32 v4, 63, v210
	v_readlane_b32 s4, v254, 25
	v_lshlrev_b32_e32 v0, 2, v4
	v_readlane_b32 s5, v254, 26
	v_readlane_b32 s10, v254, 31
	v_readlane_b32 s11, v254, 32
	v_readlane_b32 s12, v254, 33
	v_readlane_b32 s13, v254, 34
	v_ashrrev_i32_e32 v213, 31, v212
	v_lshl_add_u64 v[218:219], s[10:11], 0, v[0:1]
	v_lshl_add_u64 v[216:217], s[12:13], 0, v[0:1]
	v_lshlrev_b64 v[2:3], 9, v[212:213]
	v_lshlrev_b32_e32 v0, 3, v4
	v_readlane_b32 s4, v254, 44
	v_or_b32_e32 v2, v2, v0
	v_readlane_b32 s5, v254, 45
	v_readlane_b32 s35, v254, 21
	v_readlane_b32 s6, v254, 27
	v_lshl_add_u64 v[220:221], s[4:5], 0, v[2:3]
	v_add_u32_e32 v2, 0x100, v212
	v_ashrrev_i32_e32 v3, 31, v2
	v_lshlrev_b64 v[2:3], 9, v[2:3]
	v_or_b32_e32 v2, v2, v0
	v_lshl_add_u64 v[222:223], s[4:5], 0, v[2:3]
	v_readlane_b32 s7, v254, 28
	v_readlane_b32 s8, v254, 29
	v_readlane_b32 s9, v254, 30
	v_readlane_b32 s14, v254, 35
	v_readlane_b32 s15, v254, 36
	v_readlane_b32 s16, v254, 37
	v_readlane_b32 s17, v254, 38
	v_readlane_b32 s18, v254, 39
	v_readlane_b32 s19, v254, 40

;   #define WB(a,b) do{ if constexpr(DV2){WAIT_BAR(b);} else {WAIT_BAR(a);} }while(0)
;   #define DMA_K(t,slot) glds16(ksrc+(long)TMAP(t)*KVBLK*PQ,(unsigned)__builtin_amdgcn_readfirstlane(kdst+(slot)))
;   #define DMA_V(t,slot) glds16(vsrc+(long)TMAP(t)*KVBLK*PQ,(unsigned)__builtin_amdgcn_readfirstlane(vdst+(slot)))
;   #define DMA_V2(t,slot) do{ if constexpr(DV2) glds16(v2src+(long)TMAP(t)*KVBLK*PQ,(unsigned)__builtin_amdgcn_readfirstlane(v2dst+(slot))); }while(0)
;     ...
;   DMA_K(0,0);DMA_V(0,0);DMA_V2(0,0);DMA_K(1,SLOTB);
;   bf16x8 qr[4];
;   #pragma unroll
;   for(int d0=0;d0<4;++d0)qr[d0]=*reinterpret_cast<const bf16x8*>(&Qw[(long)r32*PQ+d0*16+hi*8]);
;   float mhat=0.f,l_reg=0.f;f32x16 o[ND];
;   #pragma unroll
;   for(int d_=0;d_<ND;++d_)o[d_]=f32x16{};
;   f32x16 negm=f32x16{}; if constexpr(!DV2) asm volatile("":"+v"(negm));
;   const f32x16 zero16=f32x16{};
;     ...
;   const int nq_r=qrow0+(wid>>1), nq_c=(wid&1)*32+r32, n_rsw=min(max(nq_r-4,0),56), n_cs=min(max(nq_c-8,0),48);
;     ...
;   bool resc=false;
;     ...
;   f32x16 pA0,pA1,pB0,pB1;
;   int sl_prev=0,sl_cur=0,sl_next=SLOTB;
;     ...
;   DMA_K(2,2*SLOTB);
;   WB(3,4);
;   qkt(pA0,pA1,Kbase,qr,NEGM,r32,hi);asm volatile("s_nop 15\n\ts_nop 7":"+v"(pA0),"+v"(pA1));CMASK(pA0,pA1,0);
;   START(pA0,pA1);
.LBB0_258:
	s_or_b32 s13, s42, s40
	s_mul_i32 s6, s13, 0x1100
	s_mul_hi_u32 s7, s13, 0x1100
	s_add_u32 s6, s6, s38
	s_addc_u32 s7, s7, 0
	s_lshl_b64 s[6:7], s[6:7], 7
	v_readlane_b32 s44, v254, 25
	v_readlane_b32 s45, v254, 26
	s_add_u32 s16, s44, s6
	v_readlane_b32 s46, v254, 27
	s_addc_u32 s17, s45, s7
	s_mul_hi_u32 s6, s13, 0x88000
	s_mul_i32 s13, s13, 0x88000
	v_mov_b32_e32 v14, v234
	v_readlane_b32 s47, v254, 28
	s_add_u32 s14, s46, s13
	s_addc_u32 s15, s47, s6
	v_readfirstlane_b32 s13, v14
	s_ashr_i32 s30, s13, 6
	s_ashr_i32 s31, s30, 31
	v_and_b32_e32 v243, 63, v14
	s_lshl_b64 s[6:7], s[30:31], 12
	s_add_u32 s16, s16, s6
	v_lshlrev_b32_e32 v0, 7, v243
	s_addc_u32 s17, s17, s7
	v_lshl_add_u64 v[2:3], s[14:15], 0, v[0:1]
	s_lshl_b32 s14, s30, 3
	s_lshl_b32 s7, s30, 4
	v_bfe_u32 v0, v14, 2, 4
	s_ashr_i32 s15, s14, 31
	v_and_or_b32 v0, s7, 48, v0
	s_ashr_i32 s7, s13, 3
	v_lshl_add_u64 v[224:225], s[14:15], 1, v[2:3]
	s_and_b32 s14, s7, 0xffffffe0
	s_ashr_i32 s15, s14, 31
	s_and_b32 s6, s13, 0x3fffffc0
	v_lshlrev_b32_e32 v0, 7, v0
	s_lshl_b64 s[14:15], s[14:15], 1
	v_lshlrev_b32_e32 v4, 3, v14
	s_lshl_b32 s43, s30, 10
	v_lshl_add_u64 v[2:3], s[10:11], 0, v[0:1]
	v_and_b32_e32 v244, 24, v4
	s_cmp_lg_u32 0, -1
	v_lshl_add_u64 v[2:3], v[2:3], 0, s[14:15]
	v_lshlrev_b32_e32 v4, 1, v244
	v_mov_b32_e32 v5, v1
	s_cselect_b32 s7, 0, 0
	v_lshl_add_u64 v[226:227], v[2:3], 0, v[4:5]
	s_add_i32 s43, s43, s7
	v_lshl_add_u64 v[2:3], s[28:29], 0, v[0:1]
	s_mov_b32 s7, m0
	s_mov_b32 m0, s43
	s_nop 0
	global_load_lds_dwordx4 v[224:225], off
	s_mov_b32 m0, s7
	v_and_b32_e32 v211, 31, v14
	s_add_i32 s44, s43, 0x6000
	v_lshl_add_u64 v[2:3], v[2:3], 0, s[14:15]
	s_mov_b32 s7, m0
	s_mov_b32 m0, s44
	s_nop 0
	global_load_lds_dwordx4 v[226:227], off
	s_mov_b32 m0, s7
	v_bfe_u32 v242, v14, 5, 1
	v_lshl_add_u64 v[228:229], v[2:3], 0, v[4:5]
	s_add_i32 s45, s43, 0x14800
	s_mov_b32 s7, m0
	s_mov_b32 m0, s45
	s_nop 0
	global_load_lds_dwordx4 v[228:229], off
	s_mov_b32 m0, s7
	v_lshlrev_b32_e32 v0, 7, v211
	v_lshl_add_u64 v[2:3], v[224:225], 0, s[86:87]
	s_add_i32 s7, s43, 0x2000
	s_mov_b32 s13, m0
	s_mov_b32 m0, s7
	s_nop 0
	global_load_lds_dwordx4 v[2:3], off
	s_mov_b32 m0, s13
	v_lshl_or_b32 v0, v242, 4, v0
	global_load_dwordx4 v[162:165], v0, s[16:17]
	global_load_dwordx4 v[158:161], v0, s[16:17] offset:32
	global_load_dwordx4 v[154:157], v0, s[16:17] offset:64
	global_load_dwordx4 v[146:149], v0, s[16:17] offset:96
	v_lshlrev_b32_e32 v0, 10, v242
	v_lshlrev_b32_e32 v2, 4, v211
	v_add3_u32 v250, 0, v0, v2
	v_lshl_add_u64 v[2:3], v[224:225], 0, s[96:97]
	s_add_i32 s7, s43, 0x4000
	s_mov_b32 s13, m0
	s_mov_b32 m0, s7
	s_nop 0
	global_load_lds_dwordx4 v[2:3], off
	s_mov_b32 m0, s13
	s_waitcnt vmcnt(4) lgkmcnt(0)
	s_barrier
	ds_read_b128 v[2:5], v250
	ds_read_b128 v[6:9], v250 offset:512
	v_lshlrev_b32_e32 v0, 1, v14
	v_and_b32_e32 v247, 32, v0
	s_lshl_b32 s6, s6, 2
	s_add_i32 s33, s6, 0
	s_mov_b32 s82, 1
	s_movk_i32 s47, 0x2000
	s_movk_i32 s46, 0x4000
	s_andn2_b64 vcc, exec, s[4:5]
	v_lshlrev_b32_e32 v252, 4, v242
	v_lshl_add_u32 v245, v211, 2, s33
	v_readlane_b32 s48, v254, 29
	v_readlane_b32 s49, v254, 30
	v_readlane_b32 s50, v254, 31
	v_readlane_b32 s51, v254, 32
	v_readlane_b32 s52, v254, 33
	v_readlane_b32 s53, v254, 34
	v_readlane_b32 s54, v254, 35
	v_readlane_b32 s55, v254, 36
	v_readlane_b32 s56, v254, 37
	v_readlane_b32 s57, v254, 38
	v_readlane_b32 s58, v254, 39
	v_readlane_b32 s59, v254, 40
	s_waitcnt vmcnt(3) lgkmcnt(1)
	v_mfma_f32_32x32x16_bf16 v[34:49], v[2:5], v[162:165], 0
	s_waitcnt lgkmcnt(0)
	v_mfma_f32_32x32x16_bf16 v[18:33], v[6:9], v[162:165], 0
	ds_read_b128 v[2:5], v250 offset:2048
	ds_read_b128 v[6:9], v250 offset:2560
	s_waitcnt vmcnt(2) lgkmcnt(1)
	v_mfma_f32_32x32x16_bf16 v[34:49], v[2:5], v[158:161], v[34:49]
	ds_read_b128 v[2:5], v250 offset:4096
	s_waitcnt lgkmcnt(1)
	v_mfma_f32_32x32x16_bf16 v[18:33], v[6:9], v[158:161], v[18:33]
	ds_read_b128 v[6:9], v250 offset:4608
	s_waitcnt vmcnt(1) lgkmcnt(1)
	v_mfma_f32_32x32x16_bf16 v[34:49], v[2:5], v[154:157], v[34:49]
	ds_read_b128 v[2:5], v250 offset:6656
	ds_read_b128 v[10:13], v250 offset:6144
	s_waitcnt lgkmcnt(2)
	v_mfma_f32_32x32x16_bf16 v[18:33], v[6:9], v[154:157], v[18:33]
	v_lshlrev_b32_e32 v6, 4, v14
	v_and_b32_e32 v0, 0xc0, v6
	v_lshl_or_b32 v246, v242, 8, v0
	v_add_u32_e32 v0, 0, v247
	v_add3_u32 v251, v0, v244, v246
	v_add_u32_e32 v249, 0x6000, v251
	s_waitcnt vmcnt(0) lgkmcnt(0)
	v_mfma_f32_32x32x16_bf16 v[34:49], v[10:13], v[146:149], v[34:49]
	v_mfma_f32_32x32x16_bf16 v[18:33], v[2:5], v[146:149], v[18:33]
	s_nop 15
	s_nop 7
	s_waitcnt vmcnt(0) lgkmcnt(0)
	s_barrier
	s_nop 0
	v_max3_f32 v2, v34, v35, v18
	v_max3_f32 v3, v36, v37, v19
	s_nop 0
	v_max3_f32 v2, v2, v20, v21
	v_max3_f32 v3, v3, v40, v41
	s_nop 0
	v_max3_f32 v2, v2, v38, v39
	v_max3_f32 v3, v3, v24, v25
	s_nop 0
	v_max3_f32 v2, v2, v22, v23
	v_max3_f32 v3, v3, v44, v45
	s_nop 0
	v_max3_f32 v2, v2, v42, v43
	v_max3_f32 v3, v3, v28, v29
	s_nop 0
	v_max3_f32 v2, v2, v26, v27
	v_max3_f32 v3, v3, v48, v49
	s_nop 0
	v_max3_f32 v2, v2, v46, v47
	v_max3_f32 v3, v3, v32, v33
	s_nop 0
	v_max3_f32 v2, v2, v30, v31
	s_nop 0
	v_max_f32_e32 v2, v2, v3
	s_nop 0
	v_mov_b32_e32 v3, v2
	s_nop 1
	v_permlane32_swap_b32_e32 v2, v3
	v_max_f32_e32 v2, v2, v3
	v_readlane_b32 s99, v255, 40
	s_cmp_eq_u32 s99, 0
	s_cbranch_scc1 .Lfsk2_start_gen
	v_mov_b32_e32 v2, s99
; #define WAIT_BAR(N) asm volatile("s_waitcnt vmcnt(" #N ") lgkmcnt(0)\n\ts_barrier":::"memory")
;   #define WB(a,b) do{ if constexpr(DV2){WAIT_BAR(b);} else {WAIT_BAR(a);} }while(0)
;   #define DMA_K(t,slot) glds16(ksrc+(long)TMAP(t)*KVBLK*PQ,(unsigned)__builtin_amdgcn_readfirstlane(kdst+(slot)))
;   #define DMA_V(t,slot) glds16(vsrc+(long)TMAP(t)*KVBLK*PQ,(unsigned)__builtin_amdgcn_readfirstlane(vdst+(slot)))
;   #define DMA_V2(t,slot) do{ if constexpr(DV2) glds16(v2src+(long)TMAP(t)*KVBLK*PQ,(unsigned)__builtin_amdgcn_readfirstlane(v2dst+(slot))); }while(0)
;   #define ROT() do{sl_prev=sl_cur;sl_cur=sl_next;sl_next=(sl_next==(NSLOT-1)*SLOTB)?0:sl_next+SLOTB;}while(0)
;     ...
;   f32x16 pA0,pA1,pB0,pB1;
;   int sl_prev=0,sl_cur=0,sl_next=SLOTB;
;     ...
;   DMA_K(2,2*SLOTB);
;   WB(3,4);
;   qkt(pA0,pA1,Kbase,qr,NEGM,r32,hi);asm volatile("s_nop 15\n\ts_nop 7":"+v"(pA0),"+v"(pA1));CMASK(pA0,pA1,0);
;   START(pA0,pA1);
;   _Pragma("unroll") for(int r=0;r<16;++r)pA1[r]=__builtin_amdgcn_exp2f(pA1[r]);
;   WAIT_BAR(0);
;   DMA_K(3,0);DMA_V(1,SLOTB);DMA_V2(1,SLOTB);
;   ROT();
;   kload8(kf,kp0+sl_cur);
;   WB(2,3);
.Lfsk2_start_gen:
	s_nop 0
	v_add_f32_e32 v248, v1, v2
	v_sub_f32_e32 v3, v34, v2
	v_sub_f32_e32 v4, v18, v2
	v_sub_f32_e32 v5, v35, v2
	v_sub_f32_e32 v6, v19, v2
	v_sub_f32_e32 v7, v36, v2
	v_sub_f32_e32 v8, v20, v2
	v_sub_f32_e32 v9, v37, v2
	v_sub_f32_e32 v10, v21, v2
	v_sub_f32_e32 v11, v38, v2
	v_sub_f32_e32 v12, v22, v2
	v_sub_f32_e32 v13, v39, v2
	v_sub_f32_e32 v14, v23, v2
	v_sub_f32_e32 v15, v40, v2
	v_sub_f32_e32 v18, v24, v2
	v_sub_f32_e32 v19, v41, v2
	v_sub_f32_e32 v20, v25, v2
	v_sub_f32_e32 v21, v42, v2
	v_sub_f32_e32 v22, v26, v2
	v_sub_f32_e32 v23, v43, v2
	v_sub_f32_e32 v24, v27, v2
	v_sub_f32_e32 v25, v44, v2
	v_sub_f32_e32 v26, v28, v2
	v_sub_f32_e32 v27, v45, v2
	v_sub_f32_e32 v28, v29, v2
	v_sub_f32_e32 v29, v46, v2
	v_sub_f32_e32 v30, v30, v2
	v_sub_f32_e32 v34, v47, v2
	v_sub_f32_e32 v31, v31, v2
	v_sub_f32_e32 v35, v48, v2
	v_sub_f32_e32 v32, v32, v2
	v_sub_f32_e32 v36, v49, v2
	v_sub_f32_e32 v2, v33, v2
	s_nop 0
	v_exp_f32_e32 v98, v3
	v_exp_f32_e32 v97, v2
	v_lshl_add_u64 v[2:3], v[224:225], 0, s[0:1]
	s_mov_b32 s6, m0
	s_mov_b32 m0, s43
	s_nop 0
	global_load_lds_dwordx4 v[2:3], off
	s_mov_b32 m0, s6
	v_lshl_add_u64 v[2:3], v[226:227], 0, s[86:87]
	s_add_i32 s6, s43, 0x8000
	s_mov_b32 s7, m0
	s_mov_b32 m0, s6
	s_nop 0
	global_load_lds_dwordx4 v[2:3], off
	s_mov_b32 m0, s7
	v_lshl_add_u64 v[2:3], v[228:229], 0, s[86:87]
	s_add_i32 s6, s43, 0x16800
	s_mov_b32 s7, m0
	s_mov_b32 m0, s6
	s_nop 0
	global_load_lds_dwordx4 v[2:3], off
	s_mov_b32 m0, s7
	ds_read_b128 v[194:197], v250 offset:8192
	ds_read_b128 v[186:189], v250 offset:8704
	ds_read_b128 v[190:193], v250 offset:10240
	ds_read_b128 v[182:185], v250 offset:10752
	ds_read_b128 v[178:181], v250 offset:12288
	ds_read_b128 v[174:177], v250 offset:12800
	ds_read_b128 v[170:173], v250 offset:14336
	ds_read_b128 v[166:169], v250 offset:14848
	v_exp_f32_e32 v99, v5
	v_exp_f32_e32 v100, v7
	v_exp_f32_e32 v101, v9
	v_exp_f32_e32 v102, v11
	v_exp_f32_e32 v103, v13
	v_exp_f32_e32 v104, v15
	v_exp_f32_e32 v105, v19
	v_exp_f32_e32 v106, v21
	v_exp_f32_e32 v107, v23
	v_exp_f32_e32 v108, v25
	v_exp_f32_e32 v109, v27
	v_exp_f32_e32 v110, v29
	v_exp_f32_e32 v111, v34
	v_exp_f32_e32 v112, v35
	v_exp_f32_e32 v113, v36
	v_exp_f32_e32 v82, v4
	v_exp_f32_e32 v83, v6
	v_exp_f32_e32 v84, v8
	v_exp_f32_e32 v85, v10
	v_exp_f32_e32 v86, v12
	v_exp_f32_e32 v87, v14
	v_exp_f32_e32 v88, v18
	v_exp_f32_e32 v89, v20
	v_exp_f32_e32 v90, v22
	v_exp_f32_e32 v91, v24
	v_exp_f32_e32 v92, v26
	v_exp_f32_e32 v93, v28
	v_exp_f32_e32 v94, v30
	v_exp_f32_e32 v95, v31
	v_exp_f32_e32 v96, v32
	s_waitcnt vmcnt(3) lgkmcnt(0)
	s_barrier
	v_cmp_gt_u32_e64 s[6:7], 32, v243
	s_cbranch_vccnz .LBB0_274
	v_mov_b32_e32 v14, v1
	v_mov_b32_e32 v15, v1
	v_mov_b32_e32 v0, v1
	v_mov_b32_e32 v2, v1
	v_mov_b32_e32 v3, v1
	v_mov_b32_e32 v4, v1
	v_mov_b32_e32 v5, v1
	v_mov_b32_e32 v6, v1
	v_mov_b32_e32 v7, v1
	v_mov_b32_e32 v8, v1
	v_mov_b32_e32 v9, v1
	v_mov_b32_e32 v10, v1
	v_mov_b32_e32 v11, v1
	v_mov_b32_e32 v12, v1
	v_mov_b32_e32 v13, v1
	v_mov_b64_e32 v[80:81], v[14:15]
	v_mov_b64_e32 v[64:65], v[14:15]
	v_mov_b64_e32 v[48:49], v[14:15]
	v_mov_b64_e32 v[32:33], v[14:15]
	s_mov_b32 s22, 0
	s_movk_i32 s13, 0x4000
	s_movk_i32 s21, 0x2000
	v_mov_b32_e32 v232, 0
	s_mov_b32 s20, 6
	s_mov_b64 s[14:15], 0
	v_mov_b64_e32 v[78:79], v[12:13]
	v_mov_b64_e32 v[76:77], v[10:11]
	v_mov_b64_e32 v[74:75], v[8:9]
	v_mov_b64_e32 v[72:73], v[6:7]
	v_mov_b64_e32 v[70:71], v[4:5]
	v_mov_b64_e32 v[68:69], v[2:3]
	v_mov_b64_e32 v[66:67], v[0:1]
	v_mov_b64_e32 v[62:63], v[12:13]
	v_mov_b64_e32 v[60:61], v[10:11]
	v_mov_b64_e32 v[58:59], v[8:9]
	v_mov_b64_e32 v[56:57], v[6:7]
	v_mov_b64_e32 v[54:55], v[4:5]
	v_mov_b64_e32 v[52:53], v[2:3]
	v_mov_b64_e32 v[50:51], v[0:1]
	v_mov_b64_e32 v[46:47], v[12:13]
	v_mov_b64_e32 v[44:45], v[10:11]
	v_mov_b64_e32 v[42:43], v[8:9]
	v_mov_b64_e32 v[40:41], v[6:7]
	v_mov_b64_e32 v[38:39], v[4:5]
	v_mov_b64_e32 v[36:37], v[2:3]
	v_mov_b64_e32 v[34:35], v[0:1]
	v_mov_b64_e32 v[30:31], v[12:13]
	v_mov_b64_e32 v[28:29], v[10:11]
	v_mov_b64_e32 v[26:27], v[8:9]
	v_mov_b64_e32 v[24:25], v[6:7]
	v_mov_b64_e32 v[22:23], v[4:5]
	v_mov_b64_e32 v[20:21], v[2:3]
	v_mov_b64_e32 v[18:19], v[0:1]
	v_readfirstlane_b32 s48, v224
	v_readfirstlane_b32 s49, v225
	v_readfirstlane_b32 s50, v226
	v_readfirstlane_b32 s51, v227
	v_readfirstlane_b32 s52, v228
	v_readfirstlane_b32 s53, v229
	s_nop 1
	v_subrev_u32_e32 v202, s48, v224
	v_subrev_u32_e32 v203, s50, v226
	v_sub_f32_e32 v208, 0, v248
	v_sub_f32_e32 v209, 0, v248
	v_sub_f32_e32 v210, 0, v248
	v_sub_f32_e32 v211, 0, v248
	v_sub_f32_e32 v212, 0, v248
	v_sub_f32_e32 v213, 0, v248
	v_sub_f32_e32 v214, 0, v248
	v_sub_f32_e32 v215, 0, v248
	v_sub_f32_e32 v216, 0, v248
	v_sub_f32_e32 v217, 0, v248
	v_sub_f32_e32 v218, 0, v248
	v_sub_f32_e32 v219, 0, v248
	v_sub_f32_e32 v220, 0, v248
	v_sub_f32_e32 v221, 0, v248
	v_sub_f32_e32 v222, 0, v248
	v_sub_f32_e32 v223, 0, v248
	v_readlane_b32 s99, v255, 40
	s_cmp_lg_u32 s99, 0
	s_cbranch_scc1 .Lfsk2_260

.LBB0_266:
	s_add_i32 s16, s47, 0x2000
	s_cmpk_lg_i32 s47, 0x4000
	s_cselect_b32 s46, s16, 0
	s_add_i32 s16, s20, 2
	s_add_u32 s14, s14, 0x4000
	s_addc_u32 s15, s15, 0
	s_cmp_ge_u32 s16, s39
	s_cbranch_scc1 .LBB0_281
	s_mov_b32 s20, s16
	s_mov_b32 s22, s13
	s_mov_b32 s21, s47
	s_mov_b32 s13, s46
	s_branch .LBB0_260
.Lfsk2_260:
	v_add_u32_e32 v0, s22, v251
	ds_read_b64_tr_b16 v[198:199], v0 offset:24576
	ds_read_b64_tr_b16 v[200:201], v0 offset:25088
	s_waitcnt lgkmcnt(9)
	v_mfma_f32_32x32x16_bf16 v[130:145], v[194:197], v[162:165], v[208:223]
	v_add_f32_e32 v230, v98, v99
	v_cvt_pk_bf16_f32 v150, v98, v99
	v_add_f32_e32 v231, v100, v101
	v_cvt_pk_bf16_f32 v151, v100, v101
	v_add_f32_e32 v230, v102, v230
	v_add_f32_e32 v231, v103, v231
	ds_read_b64_tr_b16 v[194:195], v0 offset:28672
	ds_read_b64_tr_b16 v[196:197], v0 offset:29184
	s_waitcnt lgkmcnt(10)
	v_mfma_f32_32x32x16_bf16 v[114:129], v[186:189], v[162:165], v[208:223]
	v_add_f32_e32 v230, v104, v230
	v_cvt_pk_bf16_f32 v152, v102, v103
	v_add_f32_e32 v231, v105, v231
	v_cvt_pk_bf16_f32 v153, v104, v105
	v_add_f32_e32 v230, v106, v230
	v_add_f32_e32 v231, v107, v231
	ds_read_b64_tr_b16 v[102:103], v0 offset:25600
	ds_read_b64_tr_b16 v[104:105], v0 offset:26112
	s_waitcnt lgkmcnt(11)
	v_mfma_f32_32x32x16_bf16 v[130:145], v[190:193], v[158:161], v[130:145]
	v_add_f32_e32 v230, v108, v230
	v_cvt_pk_bf16_f32 v10, v106, v107
	v_add_f32_e32 v231, v109, v231
	v_cvt_pk_bf16_f32 v11, v108, v109
	v_add_f32_e32 v230, v110, v230
	v_add_f32_e32 v231, v111, v231
	ds_read_b64_tr_b16 v[98:99], v0 offset:29696
	ds_read_b64_tr_b16 v[100:101], v0 offset:30208
	s_waitcnt lgkmcnt(12)
	v_mfma_f32_32x32x16_bf16 v[114:129], v[182:185], v[158:161], v[114:129]
	v_add_f32_e32 v230, v112, v230
	v_cvt_pk_bf16_f32 v12, v110, v111
	v_add_f32_e32 v231, v113, v231
	v_cvt_pk_bf16_f32 v13, v112, v113
	v_add_f32_e32 v230, v82, v230
	v_add_f32_e32 v231, v83, v231
	ds_read_b64_tr_b16 v[110:111], v0 offset:26624
	ds_read_b64_tr_b16 v[112:113], v0 offset:27136
	s_waitcnt lgkmcnt(13)
	v_mfma_f32_32x32x16_bf16 v[130:145], v[178:181], v[154:157], v[130:145]
	v_add_f32_e32 v230, v84, v230
	v_cvt_pk_bf16_f32 v6, v82, v83
	v_add_f32_e32 v231, v85, v231
	v_cvt_pk_bf16_f32 v7, v84, v85
	v_add_f32_e32 v230, v86, v230
	v_add_f32_e32 v231, v87, v231
	ds_read_b64_tr_b16 v[106:107], v0 offset:30720
	ds_read_b64_tr_b16 v[108:109], v0 offset:31232
	s_waitcnt lgkmcnt(14)
	v_mfma_f32_32x32x16_bf16 v[114:129], v[174:177], v[154:157], v[114:129]
	v_add_f32_e32 v230, v88, v230
	v_cvt_pk_bf16_f32 v8, v86, v87
	v_add_f32_e32 v231, v89, v231
	v_cvt_pk_bf16_f32 v9, v88, v89
	v_add_f32_e32 v230, v90, v230
	v_add_f32_e32 v231, v91, v231
	ds_read_b64_tr_b16 v[86:87], v0 offset:27648
	ds_read_b64_tr_b16 v[88:89], v0 offset:28160
	s_waitcnt lgkmcnt(14)
	v_mfma_f32_32x32x16_bf16 v[130:145], v[170:173], v[146:149], v[130:145]
	v_add_f32_e32 v230, v92, v230
	v_cvt_pk_bf16_f32 v2, v90, v91
	v_add_f32_e32 v231, v93, v231
	v_cvt_pk_bf16_f32 v3, v92, v93
	v_add_f32_e32 v230, v94, v230
	v_add_f32_e32 v231, v95, v231
	ds_read_b64_tr_b16 v[82:83], v0 offset:31744
	ds_read_b64_tr_b16 v[84:85], v0 offset:32256
	v_mfma_f32_32x32x16_bf16 v[114:129], v[166:169], v[146:149], v[114:129]
	v_add_f32_e32 v230, v96, v230
	v_cvt_pk_bf16_f32 v4, v94, v95
	v_add_f32_e32 v231, v97, v231
	v_cvt_pk_bf16_f32 v5, v96, v97
	s_add_u32 s54, s48, s14
	s_addc_u32 s55, s49, s15
	s_add_u32 s56, s54, 0x8000
	s_addc_u32 s57, s55, 0
	s_add_i32 s16, s21, s43
	s_mov_b32 m0, s16
	s_nop 0
	global_load_lds_dwordx4 v202, s[56:57]
	s_add_u32 s56, s50, s14
	s_addc_u32 s57, s51, s15
	s_add_u32 s56, s56, 0x4000
	s_addc_u32 s57, s57, 0
	s_add_i32 s16, s13, s44
	s_mov_b32 m0, s16
	s_nop 0
	global_load_lds_dwordx4 v203, s[56:57]
	s_add_u32 s58, s52, s14
	s_addc_u32 s59, s53, s15
	s_add_u32 s58, s58, 0x4000
	s_addc_u32 s59, s59, 0
	s_add_i32 s16, s13, s45
	s_mov_b32 m0, s16
	s_nop 0
	global_load_lds_dwordx4 v203, s[58:59]
	v_add_f32_e32 v230, v230, v231
	v_add_f32_e32 v206, v232, v230
.Lfsk2_261:
	v_add_u32_e32 v0, s22, v249
	v_add_u32_e32 v166, 0xe800, v0
	s_waitcnt lgkmcnt(14)
	v_mfma_f32_32x32x16_bf16 v[66:81], v[150:153], v[198:201], v[66:81]
	v_exp_f32_e32 v130, v130
	v_exp_f32_e32 v131, v131
	ds_read_b64_tr_b16 v[90:91], v0 offset:59392
	ds_read_b64_tr_b16 v[92:93], v0 offset:59904
	s_waitcnt lgkmcnt(14)
	v_mfma_f32_32x32x16_bf16 v[50:65], v[150:153], v[194:197], v[50:65]
	v_exp_f32_e32 v132, v132
	v_exp_f32_e32 v133, v133
	ds_read_b64_tr_b16 v[94:95], v0 offset:63488
	ds_read_b64_tr_b16 v[96:97], v0 offset:64000
	s_waitcnt lgkmcnt(14)
	v_mfma_f32_32x32x16_bf16 v[66:81], v[10:13], v[102:105], v[66:81]
	v_exp_f32_e32 v134, v134
	v_exp_f32_e32 v135, v135
	ds_read_b64_tr_b16 v[102:103], v0 offset:60416
	ds_read_b64_tr_b16 v[104:105], v0 offset:60928
	s_waitcnt lgkmcnt(14)
	v_mfma_f32_32x32x16_bf16 v[50:65], v[10:13], v[98:101], v[50:65]
	v_exp_f32_e32 v136, v136
	v_exp_f32_e32 v137, v137
	ds_read_b64_tr_b16 v[98:99], v0 offset:64512
	ds_read_b64_tr_b16 v[100:101], v0 offset:65024
	s_waitcnt lgkmcnt(14)
	v_mfma_f32_32x32x16_bf16 v[66:81], v[6:9], v[110:113], v[66:81]
	v_exp_f32_e32 v138, v138
	v_exp_f32_e32 v139, v139
	ds_read_b64_tr_b16 v[110:111], v0 offset:61440
	ds_read_b64_tr_b16 v[112:113], v0 offset:61952
	s_waitcnt lgkmcnt(14)
	v_mfma_f32_32x32x16_bf16 v[50:65], v[6:9], v[106:109], v[50:65]
	v_exp_f32_e32 v140, v140
	v_exp_f32_e32 v141, v141
	ds_read_b64_tr_b16 v[106:107], v166 offset:6144
	ds_read_b64_tr_b16 v[108:109], v166 offset:6656
	s_waitcnt lgkmcnt(14)
	v_mfma_f32_32x32x16_bf16 v[66:81], v[2:5], v[86:89], v[66:81]
	v_exp_f32_e32 v142, v142
	v_exp_f32_e32 v143, v143
	ds_read_b64_tr_b16 v[190:191], v0 offset:62464
	ds_read_b64_tr_b16 v[192:193], v0 offset:62976
	s_waitcnt lgkmcnt(14)
;   #define WB(a,b) do{ if constexpr(DV2){WAIT_BAR(b);} else {WAIT_BAR(a);} }while(0)
;   #define RESC() do{ if(resc){ asm volatile("s_waitcnt lgkmcnt(0)":::"memory"); \
;       _Pragma("unroll") for(int d_=0;d_<ND;++d_) _Pragma("unroll") for(int r=0;r<16;++r)o[d_][r]*=wsf[crow(r,hi)]; } }while(0)
;   #define ROT() do{sl_prev=sl_cur;sl_cur=sl_next;sl_next=(sl_next==(NSLOT-1)*SLOTB)?0:sl_next+SLOTB;}while(0)
;     ...
;   int t=1;
;   for(;t+5<NT;t+=2){
;     STEP(pB0,pB1,pA0,pA1,t,true,true,true);     WB(2,3); RESC(); ROT();
	v_mfma_f32_32x32x16_bf16 v[50:65], v[2:5], v[82:85], v[50:65]
	v_exp_f32_e32 v144, v144
	v_exp_f32_e32 v145, v145
	ds_read_b64_tr_b16 v[194:195], v166 offset:7168
	ds_read_b64_tr_b16 v[196:197], v166 offset:7680
	s_waitcnt lgkmcnt(14)
	v_mfma_f32_32x32x16_bf16 v[34:49], v[150:153], v[90:93], v[34:49]
	v_exp_f32_e32 v114, v114
	v_exp_f32_e32 v115, v115
	s_waitcnt lgkmcnt(12)
	v_mfma_f32_32x32x16_bf16 v[18:33], v[150:153], v[94:97], v[18:33]
	v_exp_f32_e32 v116, v116
	v_exp_f32_e32 v117, v117
	v_add_u32_e32 v0, s13, v250
	ds_read_b128 v[86:89], v0
	ds_read_b128 v[82:85], v0 offset:512
	s_waitcnt lgkmcnt(12)
	v_mfma_f32_32x32x16_bf16 v[34:49], v[10:13], v[102:105], v[34:49]
	v_exp_f32_e32 v118, v118
	v_exp_f32_e32 v119, v119
	ds_read_b128 v[186:189], v0 offset:2048
	ds_read_b128 v[182:185], v0 offset:2560
	s_waitcnt lgkmcnt(12)
	v_mfma_f32_32x32x16_bf16 v[18:33], v[10:13], v[98:101], v[18:33]
	v_exp_f32_e32 v120, v120
	v_exp_f32_e32 v121, v121
	ds_read_b128 v[178:181], v0 offset:4096
	ds_read_b128 v[174:177], v0 offset:4608
	s_waitcnt lgkmcnt(12)
	v_mfma_f32_32x32x16_bf16 v[34:49], v[6:9], v[110:113], v[34:49]
	v_exp_f32_e32 v122, v122
	v_exp_f32_e32 v123, v123
	ds_read_b128 v[170:173], v0 offset:6144
	ds_read_b128 v[166:169], v0 offset:6656
	s_waitcnt lgkmcnt(12)
	v_mfma_f32_32x32x16_bf16 v[18:33], v[6:9], v[106:109], v[18:33]
	v_exp_f32_e32 v124, v124
	v_exp_f32_e32 v125, v125
	s_waitcnt lgkmcnt(10)
	v_mfma_f32_32x32x16_bf16 v[34:49], v[2:5], v[190:193], v[34:49]
	v_exp_f32_e32 v126, v126
	v_exp_f32_e32 v127, v127
	s_waitcnt lgkmcnt(8)
	v_mfma_f32_32x32x16_bf16 v[18:33], v[2:5], v[194:197], v[18:33]
	v_exp_f32_e32 v128, v128
	v_exp_f32_e32 v129, v129
	s_waitcnt vmcnt(3) lgkmcnt(0)
	s_barrier
	v_add_u32_e32 v0, s33, v252
.Lfsk2_263:
	s_add_i32 s16, s13, 0x2000
	s_cmpk_lg_i32 s13, 0x4000
	s_cselect_b32 s47, s16, 0
	v_add_u32_e32 v207, s21, v251
	ds_read_b64_tr_b16 v[198:199], v207 offset:24576
	ds_read_b64_tr_b16 v[200:201], v207 offset:25088
	s_waitcnt lgkmcnt(9)
	v_mfma_f32_32x32x16_bf16 v[98:113], v[86:89], v[162:165], v[208:223]
	v_add_f32_e32 v230, v130, v131
	v_cvt_pk_bf16_f32 v150, v130, v131
	v_add_f32_e32 v231, v132, v133
	v_cvt_pk_bf16_f32 v151, v132, v133
	v_add_f32_e32 v230, v134, v230
	v_add_f32_e32 v231, v135, v231
	ds_read_b64_tr_b16 v[194:195], v207 offset:28672
	ds_read_b64_tr_b16 v[196:197], v207 offset:29184
	s_waitcnt lgkmcnt(10)
	v_mfma_f32_32x32x16_bf16 v[82:97], v[82:85], v[162:165], v[208:223]
	v_add_f32_e32 v230, v136, v230
	v_cvt_pk_bf16_f32 v152, v134, v135
	v_add_f32_e32 v231, v137, v231
	v_cvt_pk_bf16_f32 v153, v136, v137
	v_add_f32_e32 v230, v138, v230
	v_add_f32_e32 v231, v139, v231
	ds_read_b64_tr_b16 v[190:191], v207 offset:25600
	ds_read_b64_tr_b16 v[192:193], v207 offset:26112
	s_waitcnt lgkmcnt(11)
	v_mfma_f32_32x32x16_bf16 v[98:113], v[186:189], v[158:161], v[98:113]
	v_add_f32_e32 v230, v140, v230
	v_cvt_pk_bf16_f32 v10, v138, v139
	v_add_f32_e32 v231, v141, v231
	v_cvt_pk_bf16_f32 v11, v140, v141
	v_add_f32_e32 v230, v142, v230
	v_add_f32_e32 v231, v143, v231
	ds_read_b64_tr_b16 v[138:139], v207 offset:29696
	ds_read_b64_tr_b16 v[140:141], v207 offset:30208
	s_waitcnt lgkmcnt(12)
	v_mfma_f32_32x32x16_bf16 v[82:97], v[182:185], v[158:161], v[82:97]
	v_add_f32_e32 v230, v144, v230
	v_cvt_pk_bf16_f32 v12, v142, v143
	v_add_f32_e32 v231, v145, v231
	v_cvt_pk_bf16_f32 v13, v144, v145
	v_add_f32_e32 v230, v114, v230
	v_add_f32_e32 v231, v115, v231
	ds_read_b64_tr_b16 v[134:135], v207 offset:26624
	ds_read_b64_tr_b16 v[136:137], v207 offset:27136
	s_waitcnt lgkmcnt(13)
	v_mfma_f32_32x32x16_bf16 v[98:113], v[178:181], v[154:157], v[98:113]
	v_add_f32_e32 v230, v116, v230
	v_cvt_pk_bf16_f32 v6, v114, v115
	v_add_f32_e32 v231, v117, v231
	v_cvt_pk_bf16_f32 v7, v116, v117
	v_add_f32_e32 v230, v118, v230
	v_add_f32_e32 v231, v119, v231
	ds_read_b64_tr_b16 v[130:131], v207 offset:30720
	ds_read_b64_tr_b16 v[132:133], v207 offset:31232
	s_waitcnt lgkmcnt(14)
	v_mfma_f32_32x32x16_bf16 v[82:97], v[174:177], v[154:157], v[82:97]
	v_add_f32_e32 v230, v120, v230
	v_cvt_pk_bf16_f32 v8, v118, v119
	v_add_f32_e32 v231, v121, v231
	v_cvt_pk_bf16_f32 v9, v120, v121
	v_add_f32_e32 v230, v122, v230
	v_add_f32_e32 v231, v123, v231
	ds_read_b64_tr_b16 v[118:119], v207 offset:27648
	ds_read_b64_tr_b16 v[120:121], v207 offset:28160
	s_waitcnt lgkmcnt(14)
	v_mfma_f32_32x32x16_bf16 v[98:113], v[170:173], v[146:149], v[98:113]
	v_add_f32_e32 v230, v124, v230
	v_cvt_pk_bf16_f32 v2, v122, v123
	v_add_f32_e32 v231, v125, v231
	v_cvt_pk_bf16_f32 v3, v124, v125
	v_add_f32_e32 v230, v126, v230
	v_add_f32_e32 v231, v127, v231
	ds_read_b64_tr_b16 v[114:115], v207 offset:31744
	ds_read_b64_tr_b16 v[116:117], v207 offset:32256
	v_mfma_f32_32x32x16_bf16 v[82:97], v[166:169], v[146:149], v[82:97]
	v_add_f32_e32 v230, v128, v230
	v_cvt_pk_bf16_f32 v4, v126, v127
	v_add_f32_e32 v231, v129, v231
	v_cvt_pk_bf16_f32 v5, v128, v129
	s_add_u32 s56, s54, 0xa000
	s_addc_u32 s57, s55, 0
	s_add_i32 s16, s13, s43
	s_mov_b32 m0, s16
	s_nop 0
	global_load_lds_dwordx4 v202, s[56:57]
	s_add_u32 s56, s50, s14
	s_addc_u32 s57, s51, s15
	s_add_u32 s56, s56, 0x6000
	s_addc_u32 s57, s57, 0
	s_add_i32 s16, s47, s44
	s_mov_b32 m0, s16
	s_nop 0
	global_load_lds_dwordx4 v203, s[56:57]
	s_add_u32 s58, s52, s14
	s_addc_u32 s59, s53, s15
	s_add_u32 s58, s58, 0x6000
	s_addc_u32 s59, s59, 0
	s_add_i32 s16, s47, s45
	s_mov_b32 m0, s16
	s_nop 0
	global_load_lds_dwordx4 v203, s[58:59]
	v_add_f32_e32 v230, v230, v231
	v_add_f32_e32 v232, v206, v230
;   #define WB(a,b) do{ if constexpr(DV2){WAIT_BAR(b);} else {WAIT_BAR(a);} }while(0)
;   #define RESC() do{ if(resc){ asm volatile("s_waitcnt lgkmcnt(0)":::"memory"); \
;       _Pragma("unroll") for(int d_=0;d_<ND;++d_) _Pragma("unroll") for(int r=0;r<16;++r)o[d_][r]*=wsf[crow(r,hi)]; } }while(0)
;   #define ROT() do{sl_prev=sl_cur;sl_cur=sl_next;sl_next=(sl_next==(NSLOT-1)*SLOTB)?0:sl_next+SLOTB;}while(0)
;     ...
;   int t=1;
;   for(;t+5<NT;t+=2){
;     STEP(pB0,pB1,pA0,pA1,t,true,true,true);     WB(2,3); RESC(); ROT();
;     STEP(pA0,pA1,pB0,pB1,t+1,true,true,true);   WB(2,3); RESC(); ROT();
;   }
.Lfsk2_264:
	v_add_u32_e32 v14, s21, v249
	v_add_u32_e32 v15, 0xe800, v14
	s_waitcnt lgkmcnt(14)
	v_mfma_f32_32x32x16_bf16 v[66:81], v[150:153], v[198:201], v[66:81]
	v_exp_f32_e32 v98, v98
	v_exp_f32_e32 v99, v99
	ds_read_b64_tr_b16 v[122:123], v14 offset:59392
	ds_read_b64_tr_b16 v[124:125], v14 offset:59904
	s_waitcnt lgkmcnt(14)
	v_mfma_f32_32x32x16_bf16 v[50:65], v[150:153], v[194:197], v[50:65]
	v_exp_f32_e32 v100, v100
	v_exp_f32_e32 v101, v101
	ds_read_b64_tr_b16 v[126:127], v14 offset:63488
	ds_read_b64_tr_b16 v[128:129], v14 offset:64000
	s_waitcnt lgkmcnt(14)
	v_mfma_f32_32x32x16_bf16 v[66:81], v[10:13], v[190:193], v[66:81]
	v_exp_f32_e32 v102, v102
	v_exp_f32_e32 v103, v103
	ds_read_b64_tr_b16 v[142:143], v14 offset:60416
	ds_read_b64_tr_b16 v[144:145], v14 offset:60928
	s_waitcnt lgkmcnt(14)
	v_mfma_f32_32x32x16_bf16 v[50:65], v[10:13], v[138:141], v[50:65]
	v_exp_f32_e32 v104, v104
	v_exp_f32_e32 v105, v105
	ds_read_b64_tr_b16 v[138:139], v14 offset:64512
	ds_read_b64_tr_b16 v[140:141], v14 offset:65024
	s_waitcnt lgkmcnt(14)
	v_mfma_f32_32x32x16_bf16 v[66:81], v[6:9], v[134:137], v[66:81]
	v_exp_f32_e32 v106, v106
	v_exp_f32_e32 v107, v107
	ds_read_b64_tr_b16 v[134:135], v14 offset:61440
	ds_read_b64_tr_b16 v[136:137], v14 offset:61952
	s_waitcnt lgkmcnt(14)
	v_mfma_f32_32x32x16_bf16 v[50:65], v[6:9], v[130:133], v[50:65]
	v_exp_f32_e32 v108, v108
	v_exp_f32_e32 v109, v109
	ds_read_b64_tr_b16 v[130:131], v15 offset:6144
	ds_read_b64_tr_b16 v[132:133], v15 offset:6656
	s_waitcnt lgkmcnt(14)
	v_mfma_f32_32x32x16_bf16 v[66:81], v[2:5], v[118:121], v[66:81]
	v_exp_f32_e32 v110, v110
	v_exp_f32_e32 v111, v111
	ds_read_b64_tr_b16 v[118:119], v14 offset:62464
	ds_read_b64_tr_b16 v[120:121], v14 offset:62976
	s_waitcnt lgkmcnt(14)
	v_mfma_f32_32x32x16_bf16 v[50:65], v[2:5], v[114:117], v[50:65]
	v_exp_f32_e32 v112, v112
	v_exp_f32_e32 v113, v113
	ds_read_b64_tr_b16 v[114:115], v15 offset:7168
	ds_read_b64_tr_b16 v[116:117], v15 offset:7680
	s_waitcnt lgkmcnt(14)
	v_mfma_f32_32x32x16_bf16 v[34:49], v[150:153], v[122:125], v[34:49]
	v_exp_f32_e32 v82, v82
	v_exp_f32_e32 v83, v83
	s_waitcnt lgkmcnt(12)
	v_mfma_f32_32x32x16_bf16 v[18:33], v[150:153], v[126:129], v[18:33]
	v_exp_f32_e32 v84, v84
	v_exp_f32_e32 v85, v85
	v_add_u32_e32 v14, s47, v250
	ds_read_b128 v[194:197], v14
	ds_read_b128 v[186:189], v14 offset:512
	s_waitcnt lgkmcnt(12)
	v_mfma_f32_32x32x16_bf16 v[34:49], v[10:13], v[142:145], v[34:49]
	v_exp_f32_e32 v86, v86
	v_exp_f32_e32 v87, v87
	ds_read_b128 v[190:193], v14 offset:2048
	ds_read_b128 v[182:185], v14 offset:2560
	s_waitcnt lgkmcnt(12)
	v_mfma_f32_32x32x16_bf16 v[18:33], v[10:13], v[138:141], v[18:33]
	v_exp_f32_e32 v88, v88
	v_exp_f32_e32 v89, v89
	ds_read_b128 v[178:181], v14 offset:4096
	ds_read_b128 v[174:177], v14 offset:4608
	s_waitcnt lgkmcnt(12)
	v_mfma_f32_32x32x16_bf16 v[34:49], v[6:9], v[134:137], v[34:49]
	v_exp_f32_e32 v90, v90
	v_exp_f32_e32 v91, v91
	ds_read_b128 v[170:173], v14 offset:6144
	ds_read_b128 v[166:169], v14 offset:6656
	s_waitcnt lgkmcnt(12)
	v_mfma_f32_32x32x16_bf16 v[18:33], v[6:9], v[130:133], v[18:33]
	v_exp_f32_e32 v92, v92
	v_exp_f32_e32 v93, v93
	s_waitcnt lgkmcnt(10)
	v_mfma_f32_32x32x16_bf16 v[34:49], v[2:5], v[118:121], v[34:49]
	v_exp_f32_e32 v94, v94
	v_exp_f32_e32 v95, v95
	s_waitcnt lgkmcnt(8)
	v_mfma_f32_32x32x16_bf16 v[18:33], v[2:5], v[114:117], v[18:33]
	v_exp_f32_e32 v96, v96
	v_exp_f32_e32 v97, v97
	s_waitcnt vmcnt(3) lgkmcnt(0)
	s_barrier
.Lfsk2_266:
	s_add_i32 s16, s47, 0x2000
	s_cmpk_lg_i32 s47, 0x4000
	s_cselect_b32 s46, s16, 0
	s_add_i32 s16, s20, 2
	s_add_u32 s14, s14, 0x4000
	s_addc_u32 s15, s15, 0
	s_cmp_ge_u32 s16, s39
	s_cbranch_scc1 .LBB0_281
	s_mov_b32 s20, s16
	s_mov_b32 s22, s13
	s_mov_b32 s21, s47
	s_mov_b32 s13, s46
	s_branch .Lfsk2_260

;   #define WB(a,b) do{ if constexpr(DV2){WAIT_BAR(b);} else {WAIT_BAR(a);} }while(0)
;   #define DMA_K(t,slot) glds16(ksrc+(long)TMAP(t)*KVBLK*PQ,(unsigned)__builtin_amdgcn_readfirstlane(kdst+(slot)))
;   #define DMA_V(t,slot) glds16(vsrc+(long)TMAP(t)*KVBLK*PQ,(unsigned)__builtin_amdgcn_readfirstlane(vdst+(slot)))
;   #define DMA_V2(t,slot) do{ if constexpr(DV2) glds16(v2src+(long)TMAP(t)*KVBLK*PQ,(unsigned)__builtin_amdgcn_readfirstlane(v2dst+(slot))); }while(0)
;     ...
;   DMA_K(0,0);DMA_V(0,0);DMA_V2(0,0);DMA_K(1,SLOTB);
;   bf16x8 qr[4];
;   #pragma unroll
;   for(int d0=0;d0<4;++d0)qr[d0]=*reinterpret_cast<const bf16x8*>(&Qw[(long)r32*PQ+d0*16+hi*8]);
;   float mhat=0.f,l_reg=0.f;f32x16 o[ND];
;   #pragma unroll
;   for(int d_=0;d_<ND;++d_)o[d_]=f32x16{};
;   f32x16 negm=f32x16{}; if constexpr(!DV2) asm volatile("":"+v"(negm));
;   const f32x16 zero16=f32x16{};
;     ...
;   const int nq_r=qrow0+(wid>>1), nq_c=(wid&1)*32+r32, n_rsw=min(max(nq_r-4,0),56), n_cs=min(max(nq_c-8,0),48);
;     ...
;   bool resc=false;
;     ...
;   f32x16 pA0,pA1,pB0,pB1;
;   int sl_prev=0,sl_cur=0,sl_next=SLOTB;
;     ...
;   DMA_K(2,2*SLOTB);
;   WB(3,4);
;   qkt(pA0,pA1,Kbase,qr,NEGM,r32,hi);asm volatile("s_nop 15\n\ts_nop 7":"+v"(pA0),"+v"(pA1));CMASK(pA0,pA1,0);
;   START(pA0,pA1);
.LBB0_838:
	s_lshl_b32 s4, s21, 8
	v_mov_b32_e32 v0, 0x100
	s_lshr_b32 s6, s21, 4
	s_and_b32 s22, s4, 0xf00
	v_sub_co_u32_e64 v0, s[4:5], s21, v0
	s_and_b64 s[8:9], s[4:5], exec
	v_readfirstlane_b32 s7, v0
	s_cselect_b32 s23, s6, s7
	v_readlane_b32 s6, v254, 46
	s_lshr_b32 s8, s23, 2
	s_add_i32 s6, s6, s23
	s_add_i32 s11, s22, 0x100
	s_mul_hi_u32 s9, s6, 0x1100
	s_mul_i32 s10, s6, 0x1100
	s_and_b64 s[6:7], s[4:5], exec
	s_cselect_b32 s6, s11, 0
	s_add_u32 s6, s10, s6
	s_addc_u32 s7, s9, 0
	s_lshl_b64 s[6:7], s[6:7], 7
	s_add_u32 s14, s36, s6
	v_readlane_b32 s6, v254, 53
	s_addc_u32 s15, s37, s7
	s_add_i32 s6, s6, s8
	s_mul_i32 s8, s6, 0x88000
	s_mul_hi_u32 s9, s6, 0x88000
	s_add_u32 s6, s38, s8
	s_addc_u32 s7, s39, s9
	s_add_u32 s8, s40, s8
	s_addc_u32 s9, s41, s9
	v_mov_b32_e32 v50, v234
	s_and_b64 s[10:11], s[4:5], exec
	s_cselect_b32 s25, 0x44, 4
	v_readfirstlane_b32 s16, v50
	s_ashr_i32 s10, s16, 6
	s_ashr_i32 s11, s10, 31
	v_and_b32_e32 v17, 63, v50
	s_lshl_b64 s[12:13], s[10:11], 12
	s_add_u32 s12, s14, s12
	v_lshlrev_b32_e32 v0, 7, v17
	s_addc_u32 s13, s15, s13
	v_lshl_add_u64 v[2:3], s[6:7], 0, v[0:1]
	s_lshl_b32 s6, s10, 3
	s_ashr_i32 s7, s6, 31
	v_lshl_add_u64 v[186:187], s[6:7], 1, v[2:3]
	s_lshl_b32 s6, s10, 4
	v_bfe_u32 v0, v50, 2, 4
	v_and_or_b32 v0, s6, 48, v0
	s_ashr_i32 s6, s16, 3
	s_andn2_b32 s6, s6, 31
	s_and_b32 s15, s16, 0x3fffffc0
	v_lshlrev_b32_e32 v0, 7, v0
	s_ashr_i32 s7, s6, 31
	s_lshl_b32 s26, s10, 10
	v_lshl_add_u64 v[2:3], s[8:9], 0, v[0:1]
	v_lshlrev_b32_e32 v196, 3, v50
	s_cmp_lg_u32 0, -1
	v_lshl_add_u64 v[2:3], s[6:7], 1, v[2:3]
	v_and_b32_e32 v199, 24, v196
	s_cselect_b32 s6, 0, 0
	v_and_b32_e32 v197, 31, v50
	v_lshlrev_b32_e32 v0, 1, v199
	s_add_i32 s26, s26, s6
	s_mov_b32 s6, m0
	s_mov_b32 m0, s26
	s_nop 0
	global_load_lds_dwordx4 v[186:187], off
	s_mov_b32 m0, s6
	v_bfe_u32 v198, v50, 5, 1
	v_lshl_add_u64 v[98:99], v[2:3], 0, v[0:1]
	s_add_i32 s27, s26, 0x6000
	s_mov_b32 s6, m0
	s_mov_b32 m0, s27
	s_nop 0
	global_load_lds_dwordx4 v[98:99], off
	s_mov_b32 m0, s6
	v_lshlrev_b32_e32 v0, 7, v197
	v_lshl_add_u64 v[2:3], v[186:187], 0, s[86:87]
	s_add_i32 s6, s26, 0x2000
	s_mov_b32 s7, m0
	s_mov_b32 m0, s6
	s_nop 0
	global_load_lds_dwordx4 v[2:3], off
	s_mov_b32 m0, s7
	v_lshl_or_b32 v0, v198, 4, v0
	global_load_dwordx4 v[146:149], v0, s[12:13]
	global_load_dwordx4 v[142:145], v0, s[12:13] offset:32
	global_load_dwordx4 v[138:141], v0, s[12:13] offset:64
	global_load_dwordx4 v[130:133], v0, s[12:13] offset:96
	v_mov_b32_e32 v14, v1
	v_mov_b32_e32 v15, v1
	v_lshlrev_b32_e32 v0, 10, v198
	v_lshlrev_b32_e32 v18, 4, v197
	v_mov_b32_e32 v2, v1
	v_mov_b32_e32 v3, v1
	v_mov_b32_e32 v4, v1
	v_mov_b32_e32 v5, v1
	v_mov_b32_e32 v6, v1
	v_mov_b32_e32 v7, v1
	v_mov_b32_e32 v8, v1
	v_mov_b32_e32 v9, v1
	v_mov_b32_e32 v10, v1
	v_mov_b32_e32 v11, v1
	v_mov_b32_e32 v12, v1
	v_mov_b32_e32 v13, v1
	v_add3_u32 v203, 0, v0, v18
	v_mov_b32_e32 v0, v1
	v_mov_b64_e32 v[32:33], v[14:15]
	v_mov_b64_e32 v[30:31], v[12:13]
	v_mov_b64_e32 v[28:29], v[10:11]
	v_mov_b64_e32 v[26:27], v[8:9]
	v_mov_b64_e32 v[24:25], v[6:7]
	v_mov_b64_e32 v[22:23], v[4:5]
	v_mov_b64_e32 v[20:21], v[2:3]
	v_mov_b64_e32 v[18:19], v[0:1]
	v_lshl_add_u64 v[34:35], v[186:187], 0, s[96:97]
	s_add_i32 s6, s26, 0x4000
	s_mov_b32 s7, m0
	s_mov_b32 m0, s6
	s_nop 0
	global_load_lds_dwordx4 v[34:35], off
	s_mov_b32 m0, s7
	s_waitcnt vmcnt(3) lgkmcnt(0)
	s_barrier
	ds_read_b128 v[2:5], v203
	ds_read_b128 v[6:9], v203 offset:512
	v_lshlrev_b32_e32 v0, 1, v50
	v_and_b32_e32 v201, 32, v0
	s_lshl_b32 s6, s15, 2
	s_waitcnt vmcnt(3) lgkmcnt(1)
	v_mfma_f32_32x32x16_bf16 v[34:49], v[2:5], v[146:149], v[18:33]
	s_add_i32 s24, s6, 0
	s_mov_b32 s14, 0
	s_mov_b32 s82, 1
	s_movk_i32 s28, 0x2000
	s_movk_i32 s29, 0x4000
	s_andn2_b64 vcc, exec, s[4:5]
	v_lshlrev_b32_e32 v205, 4, v198
	s_waitcnt lgkmcnt(0)
	v_mfma_f32_32x32x16_bf16 v[18:33], v[6:9], v[146:149], v[18:33]
	ds_read_b128 v[2:5], v203 offset:2048
	ds_read_b128 v[6:9], v203 offset:2560
	v_lshl_add_u32 v200, v197, 2, s24
	s_waitcnt vmcnt(2) lgkmcnt(1)
	v_mfma_f32_32x32x16_bf16 v[34:49], v[2:5], v[142:145], v[34:49]
	s_waitcnt lgkmcnt(0)
	v_mfma_f32_32x32x16_bf16 v[18:33], v[6:9], v[142:145], v[18:33]
	ds_read_b128 v[2:5], v203 offset:4096
	ds_read_b128 v[6:9], v203 offset:4608
	s_waitcnt vmcnt(1) lgkmcnt(1)
	v_mfma_f32_32x32x16_bf16 v[34:49], v[2:5], v[138:141], v[34:49]
	ds_read_b128 v[2:5], v203 offset:6144
	s_waitcnt lgkmcnt(1)
	v_mfma_f32_32x32x16_bf16 v[18:33], v[6:9], v[138:141], v[18:33]
	ds_read_b128 v[6:9], v203 offset:6656
	s_waitcnt vmcnt(0) lgkmcnt(1)
	v_mfma_f32_32x32x16_bf16 v[34:49], v[2:5], v[130:133], v[34:49]
	v_lshlrev_b32_e32 v2, 4, v50
	v_and_b32_e32 v0, 0xc0, v2
	v_lshl_or_b32 v0, v198, 8, v0
	v_add_u32_e32 v2, 0, v201
	v_add3_u32 v204, v2, v199, v0
	s_waitcnt lgkmcnt(0)
	v_mfma_f32_32x32x16_bf16 v[18:33], v[6:9], v[130:133], v[18:33]
	s_nop 15
	s_nop 7
	s_nop 0
	v_max3_f32 v3, v34, v35, v18
	v_max3_f32 v4, v36, v37, v19
	s_nop 0
	v_max3_f32 v3, v3, v20, v21
	v_max3_f32 v4, v4, v40, v41
	s_nop 0
	v_max3_f32 v3, v3, v38, v39
	v_max3_f32 v4, v4, v24, v25
	s_nop 0
	v_max3_f32 v3, v3, v22, v23
	v_max3_f32 v4, v4, v44, v45
	s_nop 0
	v_max3_f32 v3, v3, v42, v43
	v_max3_f32 v4, v4, v28, v29
	s_nop 0
	v_max3_f32 v3, v3, v26, v27
	v_max3_f32 v4, v4, v48, v49
	s_nop 0
	v_max3_f32 v3, v3, v46, v47
	v_max3_f32 v4, v4, v32, v33
	s_nop 0
	v_max3_f32 v3, v3, v30, v31
	s_nop 0
	v_max_f32_e32 v3, v3, v4
	s_nop 0
	v_mov_b32_e32 v4, v3
	s_nop 1
	v_permlane32_swap_b32_e32 v3, v4
	v_max_f32_e32 v3, v3, v4
	v_readlane_b32 s99, v255, 40
	s_cmp_eq_u32 s99, 0
	s_cbranch_scc1 .Lfsk0_start_gen
	v_mov_b32_e32 v3, s99
; #define WAIT_BAR(N) asm volatile("s_waitcnt vmcnt(" #N ") lgkmcnt(0)\n\ts_barrier":::"memory")
;   #define WB(a,b) do{ if constexpr(DV2){WAIT_BAR(b);} else {WAIT_BAR(a);} }while(0)
;   #define DMA_K(t,slot) glds16(ksrc+(long)TMAP(t)*KVBLK*PQ,(unsigned)__builtin_amdgcn_readfirstlane(kdst+(slot)))
;   #define DMA_V(t,slot) glds16(vsrc+(long)TMAP(t)*KVBLK*PQ,(unsigned)__builtin_amdgcn_readfirstlane(vdst+(slot)))
;   #define DMA_V2(t,slot) do{ if constexpr(DV2) glds16(v2src+(long)TMAP(t)*KVBLK*PQ,(unsigned)__builtin_amdgcn_readfirstlane(v2dst+(slot))); }while(0)
;   #define ROT() do{sl_prev=sl_cur;sl_cur=sl_next;sl_next=(sl_next==(NSLOT-1)*SLOTB)?0:sl_next+SLOTB;}while(0)
;     ...
;   f32x16 pA0,pA1,pB0,pB1;
;   int sl_prev=0,sl_cur=0,sl_next=SLOTB;
;     ...
;   DMA_K(2,2*SLOTB);
;   WB(3,4);
;   qkt(pA0,pA1,Kbase,qr,NEGM,r32,hi);asm volatile("s_nop 15\n\ts_nop 7":"+v"(pA0),"+v"(pA1));CMASK(pA0,pA1,0);
;   START(pA0,pA1);
;   _Pragma("unroll") for(int r=0;r<16;++r)pA1[r]=__builtin_amdgcn_exp2f(pA1[r]);
;   WAIT_BAR(0);
;   DMA_K(3,0);DMA_V(1,SLOTB);DMA_V2(1,SLOTB);
;   ROT();
;   kload8(kf,kp0+sl_cur);
;   WB(2,3);
.Lfsk0_start_gen:
	s_nop 0
	v_add_f32_e32 v202, v1, v3
	v_sub_f32_e32 v4, v34, v3
	v_sub_f32_e32 v5, v18, v3
	v_sub_f32_e32 v6, v35, v3
	v_sub_f32_e32 v7, v19, v3
	v_sub_f32_e32 v8, v36, v3
	s_nop 0
	v_xor_b32_e32 v50, 0x80000000, v202
	v_mov_b32_e32 v51, v50
	v_mov_b32_e32 v52, v50
	v_mov_b32_e32 v53, v50
	v_mov_b32_e32 v54, v50
	v_mov_b32_e32 v55, v50
	v_mov_b32_e32 v56, v50
	v_mov_b32_e32 v57, v50
	v_mov_b32_e32 v58, v50
	v_mov_b32_e32 v59, v50
	v_mov_b32_e32 v60, v50
	v_mov_b32_e32 v61, v50
	v_mov_b32_e32 v62, v50
	v_mov_b32_e32 v63, v50
	v_mov_b32_e32 v64, v50
	v_mov_b32_e32 v65, v50
	v_sub_f32_e32 v9, v20, v3
	v_sub_f32_e32 v10, v37, v3
	v_sub_f32_e32 v11, v21, v3
	v_sub_f32_e32 v12, v38, v3
	v_sub_f32_e32 v13, v22, v3
	v_sub_f32_e32 v14, v39, v3
	v_sub_f32_e32 v15, v23, v3
	v_sub_f32_e32 v18, v40, v3
	v_sub_f32_e32 v19, v24, v3
	v_sub_f32_e32 v20, v41, v3
	v_sub_f32_e32 v21, v25, v3
	v_sub_f32_e32 v22, v42, v3
	v_sub_f32_e32 v23, v26, v3
	v_sub_f32_e32 v24, v43, v3
	v_sub_f32_e32 v25, v27, v3
	v_sub_f32_e32 v26, v44, v3
	v_sub_f32_e32 v27, v28, v3
	v_sub_f32_e32 v28, v45, v3
	v_sub_f32_e32 v29, v29, v3
	v_sub_f32_e32 v34, v46, v3
	v_sub_f32_e32 v30, v30, v3
	v_sub_f32_e32 v35, v47, v3
	v_sub_f32_e32 v31, v31, v3
	v_sub_f32_e32 v36, v48, v3
	v_sub_f32_e32 v32, v32, v3
	v_sub_f32_e32 v37, v49, v3
	v_sub_f32_e32 v3, v33, v3
	s_waitcnt vmcnt(0) lgkmcnt(0)
	s_barrier
	s_nop 0
	v_exp_f32_e32 v87, v14
	v_exp_f32_e32 v81, v3
	v_lshl_add_u64 v[2:3], v[186:187], 0, s[0:1]
	s_mov_b32 s6, m0
	s_mov_b32 m0, s26
	s_nop 0
	global_load_lds_dwordx4 v[2:3], off
	s_mov_b32 m0, s6
	v_exp_f32_e32 v71, v15
	v_lshl_add_u64 v[14:15], v[98:99], 0, s[86:87]
	s_add_i32 s6, s26, 0x8000
	s_mov_b32 s7, m0
	s_mov_b32 m0, s6
	s_nop 0
	global_load_lds_dwordx4 v[14:15], off
	s_mov_b32 m0, s7
	ds_read_b128 v[178:181], v203 offset:8192
	ds_read_b128 v[174:177], v203 offset:8704
	ds_read_b128 v[170:173], v203 offset:10240
	ds_read_b128 v[166:169], v203 offset:10752
	ds_read_b128 v[162:165], v203 offset:12288
	ds_read_b128 v[158:161], v203 offset:12800
	ds_read_b128 v[154:157], v203 offset:14336
	ds_read_b128 v[150:153], v203 offset:14848
	v_exp_f32_e32 v82, v4
	v_exp_f32_e32 v83, v6
	v_exp_f32_e32 v84, v8
	v_exp_f32_e32 v85, v10
	v_exp_f32_e32 v86, v12
	v_exp_f32_e32 v88, v18
	v_exp_f32_e32 v89, v20
	v_exp_f32_e32 v90, v22
	v_exp_f32_e32 v91, v24
	v_exp_f32_e32 v92, v26
	v_exp_f32_e32 v93, v28
	v_exp_f32_e32 v94, v34
	v_exp_f32_e32 v95, v35
	v_exp_f32_e32 v96, v36
	v_exp_f32_e32 v97, v37
	v_exp_f32_e32 v66, v5
	v_exp_f32_e32 v67, v7
	v_exp_f32_e32 v68, v9
	v_exp_f32_e32 v69, v11
	v_exp_f32_e32 v70, v13
	v_exp_f32_e32 v72, v19
	v_exp_f32_e32 v73, v21
	v_exp_f32_e32 v74, v23
	v_exp_f32_e32 v75, v25
	v_exp_f32_e32 v76, v27
	v_exp_f32_e32 v77, v29
	v_exp_f32_e32 v78, v30
	v_exp_f32_e32 v79, v31
	v_exp_f32_e32 v80, v32
	s_waitcnt vmcnt(2) lgkmcnt(0)
	s_barrier
	v_cmp_gt_u32_e64 s[6:7], 32, v17
	s_cbranch_vccnz .LBB0_854
	v_mov_b32_e32 v206, 0
	v_lshl_add_u64 v[188:189], v[98:99], 0, s[0:1]
	v_lshl_add_u64 v[190:191], v[186:187], 0, s[2:3]
	s_movk_i32 s14, 0x4000
	s_movk_i32 s16, 0x2000
	s_mov_b32 s8, 0
	s_mov_b32 s15, 6
	v_mov_b32_e32 v34, 0
	v_mov_b32_e32 v35, v206
	v_mov_b32_e32 v36, v206
	v_mov_b32_e32 v37, v206
	v_mov_b32_e32 v38, v206
	v_mov_b32_e32 v39, v206
	v_mov_b32_e32 v40, v206
	v_mov_b32_e32 v41, v206
	v_mov_b32_e32 v42, v206
	v_mov_b32_e32 v43, v206
	v_mov_b32_e32 v44, v206
	v_mov_b32_e32 v45, v206
	v_mov_b32_e32 v46, v206
	v_mov_b32_e32 v47, v206
	v_mov_b32_e32 v48, v206
	v_mov_b32_e32 v49, v206
	v_mov_b32_e32 v18, v206
	v_mov_b32_e32 v19, v206
	v_mov_b32_e32 v20, v206
	v_mov_b32_e32 v21, v206
	v_mov_b32_e32 v22, v206
	v_mov_b32_e32 v23, v206
	v_mov_b32_e32 v24, v206
	v_mov_b32_e32 v25, v206
	v_mov_b32_e32 v26, v206
	v_mov_b32_e32 v27, v206
	v_mov_b32_e32 v28, v206
	v_mov_b32_e32 v29, v206
	v_mov_b32_e32 v30, v206
	v_mov_b32_e32 v31, v206
	v_mov_b32_e32 v32, v206
	v_mov_b32_e32 v33, v206
	v_readfirstlane_b32 s34, v190
	v_readfirstlane_b32 s35, v191
	v_readfirstlane_b32 s36, v188
	v_readfirstlane_b32 s37, v189
	v_mov_b32_e32 v209, 0
	v_mov_b32_e32 v211, 0
	s_nop 1
	v_subrev_u32_e32 v208, s34, v190
	v_subrev_u32_e32 v210, s36, v188
	v_readlane_b32 s99, v255, 40
	s_cmp_lg_u32 s99, 0
	s_cbranch_scc1 .Lfsk0_840

.Lfsk0_840:
	v_add_u32_e32 v192, s8, v204
	ds_read_b64_tr_b16 v[182:183], v192 offset:24576
	ds_read_b64_tr_b16 v[184:185], v192 offset:25088
	s_waitcnt lgkmcnt(9)
	v_mfma_f32_32x32x16_bf16 v[114:129], v[178:181], v[146:149], v[50:65]
	v_add_f32_e32 v212, v82, v83
	v_cvt_pk_bf16_f32 v134, v82, v83
	v_add_f32_e32 v213, v84, v85
	v_cvt_pk_bf16_f32 v135, v84, v85
	v_add_f32_e32 v212, v86, v212
	v_add_f32_e32 v213, v87, v213
	ds_read_b64_tr_b16 v[178:179], v192 offset:28672
	ds_read_b64_tr_b16 v[180:181], v192 offset:29184
	s_waitcnt lgkmcnt(10)
	v_mfma_f32_32x32x16_bf16 v[98:113], v[174:177], v[146:149], v[50:65]
	v_add_f32_e32 v212, v88, v212
	v_cvt_pk_bf16_f32 v136, v86, v87
	v_add_f32_e32 v213, v89, v213
	v_cvt_pk_bf16_f32 v137, v88, v89
	v_add_f32_e32 v212, v90, v212
	v_add_f32_e32 v213, v91, v213
	ds_read_b64_tr_b16 v[82:83], v192 offset:25600
	ds_read_b64_tr_b16 v[84:85], v192 offset:26112
	s_waitcnt lgkmcnt(11)
	v_mfma_f32_32x32x16_bf16 v[114:129], v[170:173], v[142:145], v[114:129]
	v_add_f32_e32 v212, v92, v212
	v_cvt_pk_bf16_f32 v10, v90, v91
	v_add_f32_e32 v213, v93, v213
	v_cvt_pk_bf16_f32 v11, v92, v93
	v_add_f32_e32 v212, v94, v212
	v_add_f32_e32 v213, v95, v213
	ds_read_b64_tr_b16 v[86:87], v192 offset:29696
	ds_read_b64_tr_b16 v[88:89], v192 offset:30208
	s_waitcnt lgkmcnt(12)
	v_mfma_f32_32x32x16_bf16 v[98:113], v[166:169], v[142:145], v[98:113]
	v_add_f32_e32 v212, v96, v212
	v_cvt_pk_bf16_f32 v12, v94, v95
	v_add_f32_e32 v213, v97, v213
	v_cvt_pk_bf16_f32 v13, v96, v97
	v_add_f32_e32 v212, v66, v212
	v_add_f32_e32 v213, v67, v213
	ds_read_b64_tr_b16 v[90:91], v192 offset:26624
	ds_read_b64_tr_b16 v[92:93], v192 offset:27136
	s_waitcnt lgkmcnt(13)
	v_mfma_f32_32x32x16_bf16 v[114:129], v[162:165], v[138:141], v[114:129]
	v_add_f32_e32 v212, v68, v212
	v_cvt_pk_bf16_f32 v6, v66, v67
	v_add_f32_e32 v213, v69, v213
	v_cvt_pk_bf16_f32 v7, v68, v69
	v_add_f32_e32 v212, v70, v212
	v_add_f32_e32 v213, v71, v213
	ds_read_b64_tr_b16 v[66:67], v192 offset:30720
	ds_read_b64_tr_b16 v[68:69], v192 offset:31232
	s_waitcnt lgkmcnt(14)
	v_mfma_f32_32x32x16_bf16 v[98:113], v[158:161], v[138:141], v[98:113]
	v_add_f32_e32 v212, v72, v212
	v_cvt_pk_bf16_f32 v8, v70, v71
	v_add_f32_e32 v213, v73, v213
	v_cvt_pk_bf16_f32 v9, v72, v73
	v_add_f32_e32 v212, v74, v212
	v_add_f32_e32 v213, v75, v213
	ds_read_b64_tr_b16 v[70:71], v192 offset:27648
	ds_read_b64_tr_b16 v[72:73], v192 offset:28160
	s_waitcnt lgkmcnt(14)
	v_mfma_f32_32x32x16_bf16 v[114:129], v[154:157], v[130:133], v[114:129]
	v_add_f32_e32 v212, v76, v212
	v_cvt_pk_bf16_f32 v2, v74, v75
	v_add_f32_e32 v213, v77, v213
	v_cvt_pk_bf16_f32 v3, v76, v77
	v_add_f32_e32 v212, v78, v212
	v_add_f32_e32 v213, v79, v213
	ds_read_b64_tr_b16 v[74:75], v192 offset:31744
	ds_read_b64_tr_b16 v[76:77], v192 offset:32256
	v_mfma_f32_32x32x16_bf16 v[98:113], v[150:153], v[130:133], v[98:113]
	v_add_f32_e32 v212, v80, v212
	v_cvt_pk_bf16_f32 v4, v78, v79
	v_add_f32_e32 v213, v81, v213
	v_cvt_pk_bf16_f32 v5, v80, v81
	s_add_u32 s38, s34, s52
	s_addc_u32 s39, s35, s53
	s_add_i32 s8, s16, s26
	s_mov_b32 m0, s8
	s_nop 0
	global_load_lds_dwordx4 v208, s[38:39]
	s_add_u32 s40, s36, s52
	s_addc_u32 s41, s37, s53
	s_add_i32 s8, s14, s27
	s_mov_b32 m0, s8
	s_nop 0
	global_load_lds_dwordx4 v210, s[40:41]
	v_add_f32_e32 v212, v212, v213
	v_add_f32_e32 v192, v206, v212

.Lfsk0_843:
	s_add_i32 s8, s14, 0x2000
	s_cmpk_lg_i32 s14, 0x4000
	s_cselect_b32 s28, s8, 0
	v_add_u32_e32 v194, s16, v204
	ds_read_b64_tr_b16 v[154:155], v194 offset:24576
	ds_read_b64_tr_b16 v[156:157], v194 offset:25088
	s_waitcnt lgkmcnt(9)
	v_mfma_f32_32x32x16_bf16 v[82:97], v[78:81], v[146:149], v[50:65]
	v_add_f32_e32 v212, v114, v115
	v_cvt_pk_bf16_f32 v134, v114, v115
	v_add_f32_e32 v213, v116, v117
	v_cvt_pk_bf16_f32 v135, v116, v117
	v_add_f32_e32 v212, v118, v212
	v_add_f32_e32 v213, v119, v213
	ds_read_b64_tr_b16 v[150:151], v194 offset:28672
	ds_read_b64_tr_b16 v[152:153], v194 offset:29184
	s_waitcnt lgkmcnt(10)
	v_mfma_f32_32x32x16_bf16 v[66:81], v[178:181], v[146:149], v[50:65]
	v_add_f32_e32 v212, v120, v212
	v_cvt_pk_bf16_f32 v136, v118, v119
	v_add_f32_e32 v213, v121, v213
	v_cvt_pk_bf16_f32 v137, v120, v121
	v_add_f32_e32 v212, v122, v212
	v_add_f32_e32 v213, v123, v213
	ds_read_b64_tr_b16 v[114:115], v194 offset:25600
	ds_read_b64_tr_b16 v[116:117], v194 offset:26112
	s_waitcnt lgkmcnt(11)
	v_mfma_f32_32x32x16_bf16 v[82:97], v[182:185], v[142:145], v[82:97]
	v_add_f32_e32 v212, v124, v212
	v_cvt_pk_bf16_f32 v10, v122, v123
	v_add_f32_e32 v213, v125, v213
	v_cvt_pk_bf16_f32 v11, v124, v125
	v_add_f32_e32 v212, v126, v212
	v_add_f32_e32 v213, v127, v213
	ds_read_b64_tr_b16 v[118:119], v194 offset:29696
	ds_read_b64_tr_b16 v[120:121], v194 offset:30208
	s_waitcnt lgkmcnt(12)
	v_mfma_f32_32x32x16_bf16 v[66:81], v[174:177], v[142:145], v[66:81]
	v_add_f32_e32 v212, v128, v212
	v_cvt_pk_bf16_f32 v12, v126, v127
	v_add_f32_e32 v213, v129, v213
	v_cvt_pk_bf16_f32 v13, v128, v129
	v_add_f32_e32 v212, v98, v212
	v_add_f32_e32 v213, v99, v213
	ds_read_b64_tr_b16 v[122:123], v194 offset:26624
	ds_read_b64_tr_b16 v[124:125], v194 offset:27136
	s_waitcnt lgkmcnt(13)
	v_mfma_f32_32x32x16_bf16 v[82:97], v[170:173], v[138:141], v[82:97]
	v_add_f32_e32 v212, v100, v212
	v_cvt_pk_bf16_f32 v6, v98, v99
	v_add_f32_e32 v213, v101, v213
	v_cvt_pk_bf16_f32 v7, v100, v101
	v_add_f32_e32 v212, v102, v212
	v_add_f32_e32 v213, v103, v213
	ds_read_b64_tr_b16 v[98:99], v194 offset:30720
	ds_read_b64_tr_b16 v[100:101], v194 offset:31232
	s_waitcnt lgkmcnt(14)
	v_mfma_f32_32x32x16_bf16 v[66:81], v[166:169], v[138:141], v[66:81]
	v_add_f32_e32 v212, v104, v212
	v_cvt_pk_bf16_f32 v8, v102, v103
	v_add_f32_e32 v213, v105, v213
	v_cvt_pk_bf16_f32 v9, v104, v105
	v_add_f32_e32 v212, v106, v212
	v_add_f32_e32 v213, v107, v213
	ds_read_b64_tr_b16 v[102:103], v194 offset:27648
	ds_read_b64_tr_b16 v[104:105], v194 offset:28160
	s_waitcnt lgkmcnt(14)
	v_mfma_f32_32x32x16_bf16 v[82:97], v[162:165], v[130:133], v[82:97]
	v_add_f32_e32 v212, v108, v212
	v_cvt_pk_bf16_f32 v2, v106, v107
	v_add_f32_e32 v213, v109, v213
	v_cvt_pk_bf16_f32 v3, v108, v109
	v_add_f32_e32 v212, v110, v212
	v_add_f32_e32 v213, v111, v213
	ds_read_b64_tr_b16 v[106:107], v194 offset:31744
	ds_read_b64_tr_b16 v[108:109], v194 offset:32256
	v_mfma_f32_32x32x16_bf16 v[66:81], v[158:161], v[130:133], v[66:81]
	v_add_f32_e32 v212, v112, v212
	v_cvt_pk_bf16_f32 v4, v110, v111
	v_add_f32_e32 v213, v113, v213
	v_cvt_pk_bf16_f32 v5, v112, v113
	s_add_i32 s8, s14, s26
	s_mov_b32 m0, s8
	s_nop 0
	global_load_lds_dwordx4 v208, s[34:35]
	s_add_i32 s8, s28, s27
	s_mov_b32 m0, s8
	s_nop 0
	global_load_lds_dwordx4 v210, s[36:37]
	v_add_f32_e32 v212, v212, v213
	v_add_f32_e32 v206, v192, v212
;   #define WB(a,b) do{ if constexpr(DV2){WAIT_BAR(b);} else {WAIT_BAR(a);} }while(0)
;   #define RESC() do{ if(resc){ asm volatile("s_waitcnt lgkmcnt(0)":::"memory"); \
;       _Pragma("unroll") for(int d_=0;d_<ND;++d_) _Pragma("unroll") for(int r=0;r<16;++r)o[d_][r]*=wsf[crow(r,hi)]; } }while(0)
;   #define ROT() do{sl_prev=sl_cur;sl_cur=sl_next;sl_next=(sl_next==(NSLOT-1)*SLOTB)?0:sl_next+SLOTB;}while(0)
;     ...
;   int t=1;
;   for(;t+5<NT;t+=2){
;     STEP(pB0,pB1,pA0,pA1,t,true,true,true);     WB(2,3); RESC(); ROT();
;     STEP(pA0,pA1,pB0,pB1,t+1,true,true,true);   WB(2,3); RESC(); ROT();
;   }
.Lfsk0_844:
	s_waitcnt lgkmcnt(14)
	v_mfma_f32_32x32x16_bf16 v[34:49], v[134:137], v[154:157], v[34:49]
	v_exp_f32_e32 v82, v82
	v_exp_f32_e32 v83, v83
	v_exp_f32_e32 v84, v84
	v_exp_f32_e32 v85, v85
	s_waitcnt lgkmcnt(12)
	v_mfma_f32_32x32x16_bf16 v[18:33], v[134:137], v[150:153], v[18:33]
	v_exp_f32_e32 v86, v86
	v_exp_f32_e32 v87, v87
	v_exp_f32_e32 v88, v88
	v_exp_f32_e32 v89, v89
	v_add_u32_e32 v110, s28, v203
	ds_read_b128 v[178:181], v110
	ds_read_b128 v[174:177], v110 offset:512
	s_waitcnt lgkmcnt(12)
	v_mfma_f32_32x32x16_bf16 v[34:49], v[10:13], v[114:117], v[34:49]
	v_exp_f32_e32 v90, v90
	v_exp_f32_e32 v91, v91
	v_exp_f32_e32 v92, v92
	v_exp_f32_e32 v93, v93
	ds_read_b128 v[170:173], v110 offset:2048
	ds_read_b128 v[166:169], v110 offset:2560
	s_waitcnt lgkmcnt(12)
	v_mfma_f32_32x32x16_bf16 v[18:33], v[10:13], v[118:121], v[18:33]
	v_exp_f32_e32 v94, v94
	v_exp_f32_e32 v95, v95
	v_exp_f32_e32 v96, v96
	v_exp_f32_e32 v97, v97
	ds_read_b128 v[162:165], v110 offset:4096
	ds_read_b128 v[158:161], v110 offset:4608
	s_waitcnt lgkmcnt(12)
	v_mfma_f32_32x32x16_bf16 v[34:49], v[6:9], v[122:125], v[34:49]
	v_exp_f32_e32 v66, v66
	v_exp_f32_e32 v67, v67
	v_exp_f32_e32 v68, v68
	v_exp_f32_e32 v69, v69
	ds_read_b128 v[154:157], v110 offset:6144
	ds_read_b128 v[150:153], v110 offset:6656
	s_waitcnt lgkmcnt(12)
	v_mfma_f32_32x32x16_bf16 v[18:33], v[6:9], v[98:101], v[18:33]
	v_exp_f32_e32 v70, v70
	v_exp_f32_e32 v71, v71
	v_exp_f32_e32 v72, v72
	v_exp_f32_e32 v73, v73
	s_waitcnt lgkmcnt(10)
	v_mfma_f32_32x32x16_bf16 v[34:49], v[2:5], v[102:105], v[34:49]
	v_exp_f32_e32 v74, v74
	v_exp_f32_e32 v75, v75
	v_exp_f32_e32 v76, v76
	v_exp_f32_e32 v77, v77
	s_waitcnt lgkmcnt(8)
	v_mfma_f32_32x32x16_bf16 v[18:33], v[2:5], v[106:109], v[18:33]
	v_exp_f32_e32 v78, v78
	v_exp_f32_e32 v79, v79
	v_exp_f32_e32 v80, v80
	v_exp_f32_e32 v81, v81
	s_waitcnt vmcnt(2) lgkmcnt(0)
	s_barrier
.Lfsk0_846:
	s_add_i32 s8, s28, 0x2000
	s_cmpk_lg_i32 s28, 0x4000
	s_cselect_b32 s29, s8, 0
	s_add_i32 s8, s15, 2
	s_add_u32 s36, s36, 0x4000
	s_addc_u32 s37, s37, 0
	s_add_u32 s34, s34, 0x4000
	s_addc_u32 s35, s35, 0
	s_cmp_ge_u32 s8, s25
	s_cbranch_scc1 .Lattn0_steady_exit
	s_mov_b32 s15, s8
	s_mov_b32 s8, s14
	s_mov_b32 s16, s28
	s_mov_b32 s14, s29
	s_branch .Lfsk0_840
.LBB0_848:
	v_max_f32_e32 v50, v78, v78
	v_max_f32_e32 v78, 0, v50
	v_exp_f32_e64 v79, -v78
	v_add_f32_e32 v202, v202, v78
	v_xor_b32_e32 v50, 0x80000000, v202
	v_mov_b32_e32 v51, v50
	v_mov_b32_e32 v52, v50
	v_mov_b32_e32 v53, v50
	v_mov_b32_e32 v54, v50
	v_mov_b32_e32 v55, v50
	v_mov_b32_e32 v56, v50
	v_mov_b32_e32 v57, v50
	v_mov_b32_e32 v58, v50
	v_mov_b32_e32 v59, v50
	v_mov_b32_e32 v60, v50
	v_mov_b32_e32 v61, v50
	v_mov_b32_e32 v62, v50
	v_mov_b32_e32 v63, v50
	v_mov_b32_e32 v64, v50
	v_mov_b32_e32 v65, v50
	s_and_saveexec_b64 s[12:13], s[6:7]
	ds_write_b32 v200, v79 offset:49152
	s_or_b64 exec, exec, s[12:13]
	v_sub_f32_e32 v129, v129, v78
	v_sub_f32_e32 v128, v128, v78
	v_sub_f32_e32 v127, v127, v78
	v_sub_f32_e32 v126, v126, v78
	v_sub_f32_e32 v125, v125, v78
	v_sub_f32_e32 v124, v124, v78
	v_sub_f32_e32 v123, v123, v78
	v_sub_f32_e32 v122, v122, v78
	v_sub_f32_e32 v121, v121, v78
	v_sub_f32_e32 v120, v120, v78
	v_sub_f32_e32 v119, v119, v78
	v_sub_f32_e32 v118, v118, v78
	v_sub_f32_e32 v117, v117, v78
	v_sub_f32_e32 v116, v116, v78
	v_sub_f32_e32 v115, v115, v78
	v_sub_f32_e32 v114, v114, v78
	v_sub_f32_e32 v113, v113, v78
	v_sub_f32_e32 v112, v112, v78
	v_sub_f32_e32 v111, v111, v78
	v_sub_f32_e32 v110, v110, v78
	v_sub_f32_e32 v109, v109, v78
	v_sub_f32_e32 v108, v108, v78
	v_sub_f32_e32 v107, v107, v78
	v_sub_f32_e32 v106, v106, v78
	v_sub_f32_e32 v105, v105, v78
	v_sub_f32_e32 v104, v104, v78
	v_sub_f32_e32 v103, v103, v78
	v_sub_f32_e32 v102, v102, v78
	v_sub_f32_e32 v101, v101, v78
	v_sub_f32_e32 v100, v100, v78
	v_sub_f32_e32 v99, v99, v78
	v_sub_f32_e32 v98, v98, v78
	v_mul_f32_e32 v192, v192, v79
	s_branch .LBB0_841
